# hyena L1-normaliser: 16 loads in flight per round trip instead of 2 (both M1 and M2 copies)
# speedup vs baseline: 1.0061x; 1.0061x over previous
.Lnorm_1064:
	global_load_dword v144, v1, s[44:45] offset:-2048
	global_load_dword v145, v1, s[44:45]
	s_add_u32 s44, s44, 0x1000
	s_addc_u32 s45, s45, 0
	global_load_dword v146, v1, s[44:45] offset:-2048
	global_load_dword v147, v1, s[44:45]
	s_add_u32 s44, s44, 0x1000
	s_addc_u32 s45, s45, 0
	global_load_dword v148, v1, s[44:45] offset:-2048
	global_load_dword v149, v1, s[44:45]
	s_add_u32 s44, s44, 0x1000
	s_addc_u32 s45, s45, 0
	global_load_dword v150, v1, s[44:45] offset:-2048
	global_load_dword v151, v1, s[44:45]
	s_add_u32 s44, s44, 0x1000
	s_addc_u32 s45, s45, 0
	global_load_dword v152, v1, s[44:45] offset:-2048
	global_load_dword v153, v1, s[44:45]
	s_add_u32 s44, s44, 0x1000
	s_addc_u32 s45, s45, 0
	global_load_dword v154, v1, s[44:45] offset:-2048
	global_load_dword v155, v1, s[44:45]
	s_add_u32 s44, s44, 0x1000
	s_addc_u32 s45, s45, 0
	global_load_dword v156, v1, s[44:45] offset:-2048
	global_load_dword v157, v1, s[44:45]
	s_add_u32 s44, s44, 0x1000
	s_addc_u32 s45, s45, 0
	global_load_dword v158, v1, s[44:45] offset:-2048
	global_load_dword v159, v1, s[44:45]
	s_add_u32 s44, s44, 0x1000
	s_addc_u32 s45, s45, 0
	s_add_i32 s14, s14, -8
	s_waitcnt vmcnt(14)
	v_add_f32_e32 v0, v144, v145
	v_add_f32_e32 v42, v42, v0
	s_waitcnt vmcnt(12)
	v_add_f32_e32 v0, v146, v147
	v_add_f32_e32 v42, v42, v0
	s_waitcnt vmcnt(10)
	v_add_f32_e32 v0, v148, v149
	v_add_f32_e32 v42, v42, v0
	s_waitcnt vmcnt(8)
	v_add_f32_e32 v0, v150, v151
	v_add_f32_e32 v42, v42, v0
	s_waitcnt vmcnt(6)
	v_add_f32_e32 v0, v152, v153
	v_add_f32_e32 v42, v42, v0
	s_waitcnt vmcnt(4)
	v_add_f32_e32 v0, v154, v155
	v_add_f32_e32 v42, v42, v0
	s_waitcnt vmcnt(2)
	v_add_f32_e32 v0, v156, v157
	v_add_f32_e32 v42, v42, v0
	s_waitcnt vmcnt(0)
	v_add_f32_e32 v0, v158, v159
	v_add_f32_e32 v42, v42, v0
	s_cmp_eq_u32 s14, 0
	s_cbranch_scc0 .Lnorm_1064
	v_ashrrev_i32_e32 v0, 6, v7
	s_lshr_b32 s4, s13, 7
	v_cmp_gt_i32_e32 vcc, s4, v0
	s_waitcnt lgkmcnt(0)
	s_barrier
	s_and_saveexec_b64 s[48:49], vcc
	s_cbranch_execz .LBB0_961
	v_add_u32_e32 v2, 8, v0
	v_bfe_u32 v38, v7, 5, 1
	v_lshlrev_b32_e32 v5, 2, v7
	v_cmp_gt_i32_e64 s[44:45], s4, v2
	v_and_b32_e32 v2, 31, v7
	v_and_b32_e32 v39, 7, v7
	v_lshlrev_b32_e32 v3, 4, v38
	s_movk_i32 s2, 0x1190
	v_and_b32_e32 v40, 0x60, v5
	v_lshlrev_b32_e32 v41, 7, v0
	v_mad_u32_u24 v3, v39, s2, v3
	v_lshlrev_b32_e32 v4, 3, v38
	v_lshlrev_b32_e32 v5, 1, v40
	v_add3_u32 v0, v2, s13, v41
	v_add3_u32 v43, v3, v5, s9
	v_sub_u32_e32 v0, v0, v4
	v_mov_b32_e32 v2, v1
	v_mov_b32_e32 v3, v1
	v_mov_b32_e32 v4, v1
	v_mov_b32_e32 v5, v1
	v_mov_b32_e32 v6, v1
	v_mov_b32_e32 v7, v1
	v_mov_b32_e32 v8, v1
	v_mov_b32_e32 v9, v1
	v_mov_b32_e32 v10, v1
	v_mov_b32_e32 v11, v1
	v_mov_b32_e32 v12, v1
	v_mov_b32_e32 v13, v1
	v_mov_b32_e32 v14, v1
	v_mov_b32_e32 v15, v1
	s_lshr_b32 s2, s13, 4
	v_lshl_add_u32 v44, v0, 4, v251
	v_mov_b32_e32 v0, v1
	v_mov_b32_e32 v18, 0
	v_mov_b64_e32 v[16:17], v[14:15]
	s_add_i32 s4, s2, 6
	v_mov_b64_e32 v[14:15], v[12:13]
	v_mov_b64_e32 v[12:13], v[10:11]
	v_mov_b64_e32 v[10:11], v[8:9]
	v_mov_b64_e32 v[8:9], v[6:7]
	v_mov_b64_e32 v[6:7], v[4:5]
	v_mov_b64_e32 v[4:5], v[2:3]
	v_mov_b64_e32 v[2:3], v[0:1]
	v_mov_b32_e32 v19, v18
	v_mov_b32_e32 v20, v18
	v_mov_b32_e32 v21, v18
	v_mov_b32_e32 v22, v18
	v_mov_b32_e32 v23, v18
	v_mov_b32_e32 v24, v18
	v_mov_b32_e32 v25, v18
	v_mov_b32_e32 v26, v18
	v_mov_b32_e32 v27, v18
	v_mov_b32_e32 v28, v18
	v_mov_b32_e32 v29, v18
	v_mov_b32_e32 v30, v18
	v_mov_b32_e32 v31, v18
	v_mov_b32_e32 v32, v18
	v_mov_b32_e32 v33, v18
	s_branch .LBB0_1068

.Lnorm_1185:
	global_load_dword v144, v1, s[44:45] offset:-2048
	global_load_dword v145, v1, s[44:45]
	s_add_u32 s44, s44, 0x1000
	s_addc_u32 s45, s45, 0
	global_load_dword v146, v1, s[44:45] offset:-2048
	global_load_dword v147, v1, s[44:45]
	s_add_u32 s44, s44, 0x1000
	s_addc_u32 s45, s45, 0
	global_load_dword v148, v1, s[44:45] offset:-2048
	global_load_dword v149, v1, s[44:45]
	s_add_u32 s44, s44, 0x1000
	s_addc_u32 s45, s45, 0
	global_load_dword v150, v1, s[44:45] offset:-2048
	global_load_dword v151, v1, s[44:45]
	s_add_u32 s44, s44, 0x1000
	s_addc_u32 s45, s45, 0
	global_load_dword v152, v1, s[44:45] offset:-2048
	global_load_dword v153, v1, s[44:45]
	s_add_u32 s44, s44, 0x1000
	s_addc_u32 s45, s45, 0
	global_load_dword v154, v1, s[44:45] offset:-2048
	global_load_dword v155, v1, s[44:45]
	s_add_u32 s44, s44, 0x1000
	s_addc_u32 s45, s45, 0
	global_load_dword v156, v1, s[44:45] offset:-2048
	global_load_dword v157, v1, s[44:45]
	s_add_u32 s44, s44, 0x1000
	s_addc_u32 s45, s45, 0
	global_load_dword v158, v1, s[44:45] offset:-2048
	global_load_dword v159, v1, s[44:45]
	s_add_u32 s44, s44, 0x1000
	s_addc_u32 s45, s45, 0
	s_add_i32 s20, s20, -8
	s_waitcnt vmcnt(14)
	v_add_f32_e32 v0, v144, v145
	v_add_f32_e32 v38, v38, v0
	s_waitcnt vmcnt(12)
	v_add_f32_e32 v0, v146, v147
	v_add_f32_e32 v38, v38, v0
	s_waitcnt vmcnt(10)
	v_add_f32_e32 v0, v148, v149
	v_add_f32_e32 v38, v38, v0
	s_waitcnt vmcnt(8)
	v_add_f32_e32 v0, v150, v151
	v_add_f32_e32 v38, v38, v0
	s_waitcnt vmcnt(6)
	v_add_f32_e32 v0, v152, v153
	v_add_f32_e32 v38, v38, v0
	s_waitcnt vmcnt(4)
	v_add_f32_e32 v0, v154, v155
	v_add_f32_e32 v38, v38, v0
	s_waitcnt vmcnt(2)
	v_add_f32_e32 v0, v156, v157
	v_add_f32_e32 v38, v38, v0
	s_waitcnt vmcnt(0)
	v_add_f32_e32 v0, v158, v159
	v_add_f32_e32 v38, v38, v0
	s_cmp_eq_u32 s20, 0
	s_cbranch_scc0 .Lnorm_1185
	v_ashrrev_i32_e32 v0, 6, v7
	s_lshr_b32 s4, s23, 7
	v_cmp_gt_i32_e32 vcc, s4, v0
	s_waitcnt lgkmcnt(0)
	s_barrier
	s_and_saveexec_b64 s[48:49], vcc
	s_cbranch_execz .LBB0_1156
	v_add_u32_e32 v2, 8, v0
	v_bfe_u32 v41, v7, 5, 1
	v_lshlrev_b32_e32 v5, 2, v7
	v_cmp_gt_i32_e64 s[44:45], s4, v2
	v_and_b32_e32 v2, 31, v7
	v_and_b32_e32 v40, 7, v7
	v_lshlrev_b32_e32 v3, 4, v41
	s_movk_i32 s2, 0x1190
	v_and_b32_e32 v42, 0x60, v5
	v_lshlrev_b32_e32 v43, 7, v0
	v_mad_u32_u24 v3, v40, s2, v3
	v_lshlrev_b32_e32 v4, 3, v41
	v_lshlrev_b32_e32 v5, 1, v42
	v_add3_u32 v0, v2, s23, v43
	v_add3_u32 v39, v3, v5, s9
	v_sub_u32_e32 v0, v0, v4
	v_mov_b32_e32 v2, v1
	v_mov_b32_e32 v3, v1
	v_mov_b32_e32 v4, v1
	v_mov_b32_e32 v5, v1
	v_mov_b32_e32 v6, v1
	v_mov_b32_e32 v7, v1
	v_mov_b32_e32 v8, v1
	v_mov_b32_e32 v9, v1
	v_mov_b32_e32 v10, v1
	v_mov_b32_e32 v11, v1
	v_mov_b32_e32 v12, v1
	v_mov_b32_e32 v13, v1
	v_mov_b32_e32 v14, v1
	v_mov_b32_e32 v15, v1
	s_lshr_b32 s2, s23, 4
	v_lshl_add_u32 v44, v0, 4, v251
	v_mov_b32_e32 v0, v1
	v_mov_b32_e32 v18, 0
	v_mov_b64_e32 v[16:17], v[14:15]
	s_add_i32 s4, s2, 6
	v_mov_b64_e32 v[14:15], v[12:13]
	v_mov_b64_e32 v[12:13], v[10:11]
	v_mov_b64_e32 v[10:11], v[8:9]
	v_mov_b64_e32 v[8:9], v[6:7]
	v_mov_b64_e32 v[6:7], v[4:5]
	v_mov_b64_e32 v[4:5], v[2:3]
	v_mov_b64_e32 v[2:3], v[0:1]
	v_mov_b32_e32 v19, v18
	v_mov_b32_e32 v20, v18
	v_mov_b32_e32 v21, v18
	v_mov_b32_e32 v22, v18
	v_mov_b32_e32 v23, v18
	v_mov_b32_e32 v24, v18
	v_mov_b32_e32 v25, v18
	v_mov_b32_e32 v26, v18
	v_mov_b32_e32 v27, v18
	v_mov_b32_e32 v28, v18
	v_mov_b32_e32 v29, v18
	v_mov_b32_e32 v30, v18
	v_mov_b32_e32 v31, v18
	v_mov_b32_e32 v32, v18
	v_mov_b32_e32 v33, v18
	s_branch .LBB0_1189
